# grid barriers out-proj->norm and norm->in-proj made XCD-local behind a run-time placement check (every XCD = the 64 workgroups of one blockIdx&7 class), norm rows per XCD = its batch; full barriers ot
# speedup vs baseline: 1.0173x; 1.0173x over previous
; #define LAS __attribute__((address_space(3)))
; DI unsigned xb_add(unsigned* p, unsigned v) { return __hip_atomic_fetch_add(p, v, __ATOMIC_RELAXED, __HIP_MEMORY_SCOPE_AGENT); }
; DI unsigned xb_xcc_id() { return (unsigned)__builtin_amdgcn_s_getreg((3 << 11) | 20) & 0xFu; }
; DI XcdBarrier xcd_barrier_post(unsigned* bar, volatile LAS unsigned* st) {
;     XcdBarrier b; b.bar = bar; b.x = xb_xcc_id(); b.st = st;
;     if (threadIdx.x == 0) (void)xb_add(&bar[XB_XCNT(b.x)], 1u);
;     return b;
; }
; __global__ void __launch_bounds__(NTHREADS, 2) mega(Params p_, int ph_lo, int ph_hi) {
;     const Params& p = *(const Params*)__builtin_amdgcn_kernarg_segment_ptr();
;     extern __shared__ __attribute__((aligned(16))) char smem[];
;     cg::grid_group grid = cg::this_grid();
;     __shared__ uint4 xb_words;
;     if (threadIdx.x == 0) xb_words = make_uint4(0u, 0u, 0u, 0u);
;     __syncthreads();
;     XcdBarrier xb = xcd_barrier_post(p.bar, (volatile LAS unsigned*)&xb_words);
_Z4mega6Paramsii:
	v_and_b32_e32 v200, 0x3ff, v0
	v_writelane_b32 v254, s2, 0
	s_add_u32 s2, s0, 0x118
	s_addc_u32 s3, s1, 0
	v_writelane_b32 v254, s2, 1
	v_cmp_eq_u32_e64 s[54:55], 0, v200
	s_nop 0
	v_writelane_b32 v254, s3, 2
	s_and_saveexec_b64 s[4:5], s[54:55]
	v_mov_b32_e32 v2, 0
	v_mov_b32_e32 v3, v2
	v_mov_b32_e32 v4, v2
	v_mov_b32_e32 v5, v2
	ds_write_b128 v2, v[2:5]
	s_or_b64 exec, exec, s[4:5]
	s_load_dwordx2 s[66:67], s[0:1], 0x118
	s_waitcnt lgkmcnt(0)
	s_barrier
	s_load_dwordx2 s[68:69], s[0:1], 0x108
	s_getreg_b32 s2, hwreg(HW_REG_XCC_ID, 0, 4)
	s_and_b32 s3, s2, 15
	s_and_saveexec_b64 s[4:5], s[54:55]
	s_cbranch_execz .LBB0_5
	s_mov_b64 s[6:7], exec
	v_mbcnt_lo_u32_b32 v1, s6, 0
	v_mbcnt_hi_u32_b32 v1, s7, v1
	v_cmp_eq_u32_e32 vcc, 0, v1
	s_and_b64 s[8:9], exec, vcc
	s_mov_b64 exec, s[8:9]
	s_cbranch_execz .LBB0_5
	s_lshl_b32 s2, s3, 8
	s_bcnt1_i32_b64 s6, s[6:7]
	v_mov_b32_e32 v1, s2
	v_mov_b32_e32 v2, s6
	s_waitcnt lgkmcnt(0)
	v_readlane_b32 s7, v254, 0
	s_and_b32 s7, s7, 7
	s_lshl_b32 s7, 1, s7
	v_mov_b32_e32 v3, s7
	global_atomic_or v1, v3, s[68:69] offset:1028
	s_waitcnt vmcnt(0)
	global_atomic_add v1, v2, s[68:69] offset:1024

; DI int otid() { int t = threadIdx.x; asm volatile("" : "+v"(t)); return t; }
; DI void norm_phase(const Params& p, int l) {
;     const int tid_ = otid(), lane = tid_ & 63, wave = tid_ >> 6;
;     const int gw = blockIdx.x * 4 + wave, nw = gridDim.x * 4;
;     const float* g = p.norm_g + l * D;
;     float4 gg[4];
; #pragma unroll
;     for (int j = 0; j < 4; ++j) gg[j] = *(const float4*)(g + 256 * j + 4 * lane);
;     for (int row0 = gw; row0 < NTOK; row0 += 3 * nw) {
;         float4 v[3][4];
;         const float* md[3];
; #pragma unroll
;         for (int u = 0; u < 3; ++u) {
;             const int row = row0 + u * nw;
;             const int rc = row < NTOK ? row : gw;
;             const int b = rc / TPB, t = rc % TPB;
;             const float* src = src_row(p, l, b, t);
;             md[u] = p.mod + ((size_t)l * 9 + (t < SEQ ? b : 8)) * 3072;
; #pragma unroll
;             for (int j = 0; j < 4; ++j) v[u][j] = *(const float4*)(src + 256 * j + 4 * lane);
;         }
.LBB0_137:
	s_andn2_b64 vcc, exec, s[4:5]
	s_cbranch_vccnz .LBB0_292
	s_cmp_eq_u32 s98, 1
	s_mov_b64 s[4:5], -1
	s_cbranch_scc1 .LBB0_183
	v_mov_b32_e32 v16, v200
	v_readlane_b32 s4, v254, 21
	v_readlane_b32 s100, v254, 22
	s_mov_b32 s101, 0x47ff
	s_cmp_lg_u32 s100, 0x800
	s_cbranch_scc1 .Lnorm_nomap
	s_lshr_b32 s100, s4, 5
	s_lshl_b32 s100, s100, 2
	s_bfe_u32 s4, s4, 0x30002
	s_mulk_i32 s4, 0x900
	s_add_i32 s101, s4, 0x8ff
	s_add_i32 s4, s4, s100
	s_movk_i32 s100, 0x100
.Lnorm_nomap:
	v_ashrrev_i32_e32 v0, 6, v16
	s_nop 0
	v_add_u32_e32 v65, s4, v0
	s_movk_i32 s4, 0x4800
	v_cmp_gt_i32_e32 vcc, s4, v65
	s_and_saveexec_b64 s[62:63], vcc
	s_cbranch_execz .LBB0_182
	s_load_dwordx2 s[4:5], s[0:1], 0x20
	s_load_dwordx2 s[98:99], s[0:1], 0x10
	s_lshl_b32 s6, s60, 10
	s_ashr_i32 s7, s6, 31
	v_lshlrev_b32_e32 v17, 2, v16
	s_lshl_b64 s[6:7], s[6:7], 2
	s_waitcnt lgkmcnt(0)
	s_add_u32 s4, s4, s6
	v_and_b32_e32 v64, 0xfc, v17
	s_addc_u32 s5, s5, s7
	v_lshlrev_b32_e32 v12, 2, v64
	global_load_dwordx4 v[0:3], v12, s[4:5]
	global_load_dwordx4 v[4:7], v12, s[4:5] offset:1024
	global_load_dwordx4 v[8:11], v12, s[4:5] offset:2048
	s_nop 0
	global_load_dwordx4 v[12:15], v12, s[4:5] offset:3072
	v_and_b32_e32 v18, 64, v205
	v_add_u32_e32 v18, 64, v18
	v_xor_b32_e32 v19, 1, v205
	v_cmp_lt_i32_e32 vcc, v19, v18
	s_load_dwordx2 s[4:5], s[0:1], 0x0
	s_load_dwordx2 s[34:35], s[0:1], 0xb8
	s_load_dwordx2 s[28:29], s[0:1], 0xe0
	s_load_dwordx4 s[56:59], s[0:1], 0xa8
	v_cndmask_b32_e32 v19, v205, v19, vcc
	v_lshlrev_b32_e32 v79, 2, v19
	v_xor_b32_e32 v19, 2, v205
	v_cmp_lt_i32_e32 vcc, v19, v18
	v_bfe_u32 v17, v17, 5, 3
	v_lshlrev_b32_e32 v16, 3, v16
	v_cndmask_b32_e32 v19, v205, v19, vcc
	v_lshlrev_b32_e32 v84, 2, v19
	v_xor_b32_e32 v19, 4, v205
	v_cmp_lt_i32_e32 vcc, v19, v18
	v_readlane_b32 s6, v255, 34
	v_and_b32_e32 v192, 56, v16
	v_cndmask_b32_e32 v19, v205, v19, vcc
	v_lshlrev_b32_e32 v85, 2, v19
	v_xor_b32_e32 v19, 8, v205
	v_cmp_lt_i32_e32 vcc, v19, v18
	v_readlane_b32 s7, v255, 35
	s_cmp_gt_u32 s6, 4
	v_cndmask_b32_e32 v19, v205, v19, vcc
	v_lshlrev_b32_e32 v86, 2, v19
	v_xor_b32_e32 v19, 16, v205
	v_cmp_lt_i32_e32 vcc, v19, v18
	s_cselect_b64 s[6:7], -1, 0
	s_mul_hi_i32 s9, s60, 9
	v_cndmask_b32_e32 v19, v205, v19, vcc
	v_lshlrev_b32_e32 v87, 2, v19
	v_xor_b32_e32 v19, 32, v205
	v_cmp_lt_i32_e32 vcc, v19, v18
	s_mul_i32 s8, s60, 9
	v_mov_b32_e32 v68, v65
	v_cndmask_b32_e32 v18, v205, v19, vcc
	v_lshlrev_b32_e32 v88, 2, v18
	v_mul_u32_u24_e32 v18, 0x90000, v17
	s_waitcnt lgkmcnt(0)
	v_lshl_add_u64 v[16:17], s[34:35], 0, v[192:193]
	v_lshlrev_b32_e32 v192, 1, v18
	v_lshl_add_u64 v[66:67], v[16:17], 0, v[192:193]
	s_mov_b64 s[34:35], 0
	s_branch .LBB0_142
.LBB0_141:
	s_or_b64 exec, exec, s[44:45]
	s_mul_i32 s40, s100, 3
	v_add_u32_e32 v68, s40, v68
	v_cmp_lt_i32_e32 vcc, s101, v68
	s_or_b64 s[34:35], vcc, s[34:35]
	s_andn2_b64 exec, exec, s[34:35]
	s_cbranch_execz .LBB0_182

; DI void norm_phase(const Params& p, int l) {
;     ...
; #pragma unroll
;         for (int u = 0; u < 3; ++u) {
;             const int row = row0 + u * nw;
;             const int rc = row < NTOK ? row : gw;
;             const int b = rc / TPB, t = rc % TPB;
;             const float* src = src_row(p, l, b, t);
;             md[u] = p.mod + ((size_t)l * 9 + (t < SEQ ? b : 8)) * 3072;
; #pragma unroll
;             for (int j = 0; j < 4; ++j) v[u][j] = *(const float4*)(src + 256 * j + 4 * lane);
.LBB0_154:
	v_ashrrev_i32_e32 v17, 31, v16
	v_lshlrev_b64 v[20:21], v24, v[16:17]
	v_lshl_add_u64 v[18:19], v[18:19], 0, v[20:21]
	v_lshlrev_b64 v[20:21], 12, v[22:23]
	v_lshl_add_u64 v[18:19], v[18:19], 0, v[20:21]
	v_lshlrev_b32_e32 v192, 2, v64
	v_lshl_add_u64 v[18:19], v[18:19], 0, v[192:193]
	global_load_dwordx4 v[60:63], v[18:19], off
	global_load_dwordx4 v[56:59], v[18:19], off offset:1024
	global_load_dwordx4 v[52:55], v[18:19], off offset:2048
	global_load_dwordx4 v[48:51], v[18:19], off offset:3072
	s_mov_b32 s40, s100
	s_andn2_b64 vcc, exec, s[6:7]
	s_mov_b64 s[42:43], -1
	v_add_u32_e32 v74, s40, v68
	s_movk_i32 s40, 0x4800
	v_cmp_gt_i32_e64 s[46:47], s40, v74
	s_mov_b32 s40, 0x38e38e39
	s_nop 0
	v_cndmask_b32_e64 v17, v65, v74, s[46:47]
	v_mul_hi_i32 v18, v17, s40
	v_lshrrev_b32_e32 v19, 31, v18
	v_ashrrev_i32_e32 v18, 9, v18
	v_add_u32_e32 v76, v18, v19
	v_mul_i32_i24_e32 v18, 0x900, v76
	v_sub_u32_e32 v20, v17, v18
	v_cndmask_b32_e64 v17, 0, 1, s[6:7]
	v_cmp_gt_i32_e64 s[44:45], s61, v20
	v_cmp_lt_i32_e64 s[40:41], s21, v20
	v_cmp_ne_u32_e64 s[50:51], 1, v17
	s_cbranch_vccnz .LBB0_160
	v_mov_b64_e32 v[18:19], s[56:57]
	s_and_saveexec_b64 s[42:43], s[40:41]
	s_xor_b64 s[42:43], exec, s[42:43]
	v_add_u32_e32 v22, 0xfffff800, v20
	v_mov_b32_e32 v23, v193
	v_mov_b64_e32 v[18:19], s[58:59]
	s_or_saveexec_b64 s[42:43], s[42:43]
	v_mov_b64_e32 v[24:25], 20
	s_xor_b64 exec, exec, s[42:43]
	v_ashrrev_i32_e32 v21, 31, v20
	v_mov_b64_e32 v[24:25], 23
	v_mov_b64_e32 v[22:23], v[20:21]
	s_or_b64 exec, exec, s[42:43]
	s_mov_b64 s[42:43], 0

; DI void norm_phase(const Params& p, int l) {
;     ...
; #pragma unroll
;         for (int u = 0; u < 3; ++u) {
;             const int row = row0 + u * nw;
;             const int rc = row < NTOK ? row : gw;
;             const int b = rc / TPB, t = rc % TPB;
;             const float* src = src_row(p, l, b, t);
;             md[u] = p.mod + ((size_t)l * 9 + (t < SEQ ? b : 8)) * 3072;
; #pragma unroll
;             for (int j = 0; j < 4; ++j) v[u][j] = *(const float4*)(src + 256 * j + 4 * lane);
.LBB0_166:
	v_ashrrev_i32_e32 v77, 31, v76
	v_lshlrev_b64 v[20:21], v24, v[76:77]
	v_lshl_add_u64 v[18:19], v[18:19], 0, v[20:21]
	v_lshlrev_b64 v[20:21], 12, v[22:23]
	v_lshl_add_u64 v[18:19], v[18:19], 0, v[20:21]
	v_lshl_add_u64 v[18:19], v[18:19], 0, v[192:193]
	global_load_dwordx4 v[44:47], v[18:19], off
	global_load_dwordx4 v[40:43], v[18:19], off offset:1024
	global_load_dwordx4 v[36:39], v[18:19], off offset:2048
	s_waitcnt lgkmcnt(0)
	global_load_dwordx4 v[32:35], v[18:19], off offset:3072
	s_nop 0
	s_and_b64 vcc, exec, s[50:51]
	s_mov_b64 s[50:51], -1
	v_add_u32_e32 v70, s100, v68
	v_add_u32_e32 v70, s100, v70
	s_movk_i32 s40, 0x4800
	v_cmp_gt_i32_e64 s[42:43], s40, v70
	s_mov_b32 s40, 0x38e38e39
	s_nop 0
	v_cndmask_b32_e64 v17, v65, v70, s[42:43]
	v_mul_hi_i32 v18, v17, s40
	v_lshrrev_b32_e32 v19, 31, v18
	v_ashrrev_i32_e32 v18, 9, v18
	v_add_u32_e32 v72, v18, v19
	v_mul_i32_i24_e32 v18, 0x900, v72
	v_sub_u32_e32 v22, v17, v18
	v_cmp_gt_i32_e64 s[40:41], s61, v22
	v_cmp_lt_i32_e64 s[52:53], s21, v22
	s_cbranch_vccnz .LBB0_172
	v_mov_b64_e32 v[18:19], s[56:57]
	s_and_saveexec_b64 s[50:51], s[52:53]
	s_xor_b64 s[50:51], exec, s[50:51]
	v_add_u32_e32 v20, 0xfffff800, v22
	v_mov_b32_e32 v21, v193
	v_mov_b64_e32 v[18:19], s[58:59]
	s_or_saveexec_b64 s[50:51], s[50:51]
	v_mov_b64_e32 v[24:25], 20
	s_xor_b64 exec, exec, s[50:51]
	v_ashrrev_i32_e32 v23, 31, v22
	v_mov_b64_e32 v[24:25], 23
	v_mov_b64_e32 v[20:21], v[22:23]
	s_or_b64 exec, exec, s[50:51]
	s_mov_b64 s[50:51], 0

; DI unsigned xb_ld(unsigned* p)              { return __hip_atomic_load(p, __ATOMIC_RELAXED, __HIP_MEMORY_SCOPE_AGENT); }
; DI void xcd_barrier_complete(unsigned* bar, unsigned x, unsigned& nloc, unsigned& nx) {
;     const unsigned G = gridDim.x * gridDim.y * gridDim.z;
;     unsigned sum, cnt, mine, sp = 0u;
;     for (;;) {
;         sum = 0u; cnt = 0u; mine = 0u;
; #pragma unroll
;         for (unsigned j = 0; j < 16; ++j) { const unsigned c = xb_ld(&bar[XB_XCNT(j)]); sum += c; cnt += (c > 0u) ? 1u : 0u; mine = (j == x) ? c : mine; }
;         if (sum == G) break;
;         __builtin_amdgcn_s_sleep(1);
;         if ((++sp & 255u) == 0u) { if (xb_ld(&bar[XB_TMO])) break; if (sp > XB_SPIN_CAP) { atomicAdd(&bar[XB_TMO], 1u); break; } }
;     }
;     nloc = mine > 0u ? mine : 1u; nx = cnt > 0u ? cnt : 1u;
; }
; DI void xcd_barrier(const XcdBarrier& b) {
;     asm volatile("s_waitcnt vmcnt(0)" ::: "memory");
;     __syncthreads();
;     if (threadIdx.x == 0) {
;         unsigned* bar = b.bar;
;         __builtin_amdgcn_s_waitcnt(0);
;         unsigned nloc = b.st[0], nx = b.st[1];
;         if (nloc == 0u) { xcd_barrier_complete(bar, b.x, nloc, nx); b.st[0] = nloc; b.st[1] = nx; }
.LBB0_368:
	v_readlane_b32 s6, v255, 7
	v_readlane_b32 s7, v255, 8
	v_cmp_ne_u32_e32 vcc, 0, v11
	s_nop 0
	v_cndmask_b32_e64 v16, 0, v11, s[6:7]
	v_readlane_b32 s6, v255, 5
	v_readlane_b32 s7, v255, 6
	v_cndmask_b32_e64 v11, 0, 1, vcc
	v_cmp_ne_u32_e32 vcc, 0, v0
	v_cndmask_b32_e64 v16, v16, v0, s[6:7]
	v_readlane_b32 s6, v255, 3
	v_readlane_b32 s7, v255, 4
	v_addc_co_u32_e32 v0, vcc, 0, v11, vcc
	s_nop 0
	v_cndmask_b32_e64 v16, v16, v1, s[6:7]
	v_readlane_b32 s6, v255, 1
	v_readlane_b32 s7, v255, 2
	v_cmp_ne_u32_e32 vcc, 0, v1
	s_nop 0
	v_cndmask_b32_e64 v16, v16, v2, s[6:7]
	v_readlane_b32 s6, v254, 63
	v_readlane_b32 s7, v255, 0
	v_cndmask_b32_e64 v1, 0, 1, vcc
	v_cmp_ne_u32_e32 vcc, 0, v2
	v_cndmask_b32_e64 v16, v16, v3, s[6:7]
	v_readlane_b32 s6, v254, 61
	v_readlane_b32 s7, v254, 62
	v_addc_co_u32_e32 v0, vcc, v0, v1, vcc
	s_nop 0
	v_cndmask_b32_e64 v16, v16, v4, s[6:7]
	v_readlane_b32 s6, v254, 59
	v_readlane_b32 s7, v254, 60
	v_cmp_ne_u32_e32 vcc, 0, v3
	s_nop 0
	v_cndmask_b32_e64 v16, v16, v5, s[6:7]
	v_readlane_b32 s6, v254, 57
	v_readlane_b32 s7, v254, 58
	v_cndmask_b32_e64 v1, 0, 1, vcc
	v_cmp_ne_u32_e32 vcc, 0, v4
	v_cndmask_b32_e64 v16, v16, v6, s[6:7]
	v_readlane_b32 s6, v254, 55
	v_readlane_b32 s7, v254, 56
	v_addc_co_u32_e32 v0, vcc, v0, v1, vcc
	s_nop 0
	v_cndmask_b32_e64 v16, v16, v7, s[6:7]
	v_readlane_b32 s6, v254, 53
	v_cmp_ne_u32_e32 vcc, 0, v5
	v_readlane_b32 s7, v254, 54
	s_nop 0
	v_cndmask_b32_e64 v1, 0, 1, vcc
	v_cmp_ne_u32_e32 vcc, 0, v6
	v_cndmask_b32_e64 v16, v16, v8, s[6:7]
	v_readlane_b32 s6, v254, 51
	v_addc_co_u32_e32 v0, vcc, v0, v1, vcc
	v_readlane_b32 s7, v254, 52
	v_cmp_ne_u32_e32 vcc, 0, v7
	s_nop 0
	v_cndmask_b32_e64 v16, v16, v9, s[6:7]
	v_readlane_b32 s6, v254, 49
	v_cndmask_b32_e64 v1, 0, 1, vcc
	v_cmp_ne_u32_e32 vcc, 0, v8
	v_readlane_b32 s7, v254, 50
	s_nop 0
	v_addc_co_u32_e32 v0, vcc, v0, v1, vcc
	v_cndmask_b32_e64 v16, v16, v10, s[6:7]
	v_readlane_b32 s6, v254, 47
	v_cmp_ne_u32_e32 vcc, 0, v9
	v_readlane_b32 s7, v254, 48
	s_nop 0
	v_cndmask_b32_e64 v1, 0, 1, vcc
	v_cmp_ne_u32_e32 vcc, 0, v10
	v_cndmask_b32_e64 v16, v16, v12, s[6:7]
	v_readlane_b32 s6, v254, 45
	v_addc_co_u32_e32 v0, vcc, v0, v1, vcc
	v_readlane_b32 s7, v254, 46
	v_cmp_ne_u32_e32 vcc, 0, v12
	s_nop 0
	v_cndmask_b32_e64 v16, v16, v13, s[6:7]
	v_readlane_b32 s6, v254, 43
	v_cndmask_b32_e64 v1, 0, 1, vcc
	v_cmp_ne_u32_e32 vcc, 0, v13
	v_readlane_b32 s7, v254, 44
	s_nop 0
	v_addc_co_u32_e32 v0, vcc, v0, v1, vcc
	v_cndmask_b32_e64 v16, v16, v14, s[6:7]
	v_readlane_b32 s6, v254, 41
	v_cmp_ne_u32_e32 vcc, 0, v14
	v_readlane_b32 s7, v254, 42
	s_nop 0
	v_cndmask_b32_e64 v1, 0, 1, vcc
	v_cmp_ne_u32_e32 vcc, 0, v15
	v_cndmask_b32_e64 v16, v16, v15, s[6:7]
	v_max_u32_e32 v2, 1, v16
	v_addc_co_u32_e32 v0, vcc, v0, v1, vcc
	v_max_u32_e32 v0, 1, v0
	ds_write_b32 v193, v2
	ds_write_b32 v193, v0 offset:4
	v_mov_b32_e32 v17, 0x800
	v_mov_b32_e32 v50, 1
	global_load_dword v18, v193, s[68:69] offset:1024 sc1
	global_load_dword v19, v193, s[68:69] offset:1028 sc1
	global_load_dword v20, v193, s[68:69] offset:1280 sc1
	global_load_dword v21, v193, s[68:69] offset:1284 sc1
	global_load_dword v22, v193, s[68:69] offset:1536 sc1
	global_load_dword v23, v193, s[68:69] offset:1540 sc1
	global_load_dword v24, v193, s[68:69] offset:1792 sc1
	global_load_dword v25, v193, s[68:69] offset:1796 sc1
	global_load_dword v26, v193, s[68:69] offset:2048 sc1
	global_load_dword v27, v193, s[68:69] offset:2052 sc1
	global_load_dword v28, v193, s[68:69] offset:2304 sc1
	global_load_dword v29, v193, s[68:69] offset:2308 sc1
	global_load_dword v30, v193, s[68:69] offset:2560 sc1
	global_load_dword v31, v193, s[68:69] offset:2564 sc1
	global_load_dword v32, v193, s[68:69] offset:2816 sc1
	global_load_dword v33, v193, s[68:69] offset:2820 sc1
	global_load_dword v34, v193, s[68:69] offset:3072 sc1
	global_load_dword v35, v193, s[68:69] offset:3076 sc1
	global_load_dword v36, v193, s[68:69] offset:3328 sc1
	global_load_dword v37, v193, s[68:69] offset:3332 sc1
	global_load_dword v38, v193, s[68:69] offset:3584 sc1
	global_load_dword v39, v193, s[68:69] offset:3588 sc1
	global_load_dword v40, v193, s[68:69] offset:3840 sc1
	global_load_dword v41, v193, s[68:69] offset:3844 sc1
	global_load_dword v42, v17, s[68:69] offset:2048 sc1
	global_load_dword v43, v17, s[68:69] offset:2052 sc1
	global_load_dword v44, v17, s[68:69] offset:2304 sc1
	global_load_dword v45, v17, s[68:69] offset:2308 sc1
	global_load_dword v46, v17, s[68:69] offset:2560 sc1
	global_load_dword v47, v17, s[68:69] offset:2564 sc1
	global_load_dword v48, v17, s[68:69] offset:2816 sc1
	global_load_dword v49, v17, s[68:69] offset:2820 sc1
	s_waitcnt vmcnt(0)
; DI unsigned xb_add(unsigned* p, unsigned v) { return __hip_atomic_fetch_add(p, v, __ATOMIC_RELAXED, __HIP_MEMORY_SCOPE_AGENT); }
; DI void xcd_barrier(const XcdBarrier& b) {
;     asm volatile("s_waitcnt vmcnt(0)" ::: "memory");
;     __syncthreads();
;     if (threadIdx.x == 0) {
;         unsigned* bar = b.bar;
;         __builtin_amdgcn_s_waitcnt(0);
;         unsigned nloc = b.st[0], nx = b.st[1];
;         if (nloc == 0u) { xcd_barrier_complete(bar, b.x, nloc, nx); b.st[0] = nloc; b.st[1] = nx; }
;         const unsigned old = xb_add(&bar[XB_XSUB(b.x)], 1u);
;         const unsigned gen = old / nloc;
;         if (old + 1u == (gen + 1u) * nloc) {
	v_add_u32_e32 v51, -1, v19
	v_and_b32_e32 v51, v51, v19
	v_cmp_eq_u32_e32 vcc, 0, v51
	s_mov_b64 s[6:7], vcc
	v_cmp_ne_u32_e32 vcc, 0, v19
	s_and_b64 s[6:7], s[6:7], vcc
	v_cmp_eq_u32_e32 vcc, 64, v18
	s_and_b64 s[6:7], s[6:7], vcc
	v_cmp_eq_u32_e32 vcc, 0, v18
	s_or_b64 s[6:7], s[6:7], vcc
	s_nop 1
	v_cndmask_b32_e64 v50, 0, v50, s[6:7]
	v_add_u32_e32 v51, -1, v21
	v_and_b32_e32 v51, v51, v21
	v_cmp_eq_u32_e32 vcc, 0, v51
	s_mov_b64 s[6:7], vcc
	v_cmp_ne_u32_e32 vcc, 0, v21
	s_and_b64 s[6:7], s[6:7], vcc
	v_cmp_eq_u32_e32 vcc, 64, v20
	s_and_b64 s[6:7], s[6:7], vcc
	v_cmp_eq_u32_e32 vcc, 0, v20
	s_or_b64 s[6:7], s[6:7], vcc
	s_nop 1
	v_cndmask_b32_e64 v50, 0, v50, s[6:7]
	v_add_u32_e32 v51, -1, v23
	v_and_b32_e32 v51, v51, v23
	v_cmp_eq_u32_e32 vcc, 0, v51
	s_mov_b64 s[6:7], vcc
	v_cmp_ne_u32_e32 vcc, 0, v23
	s_and_b64 s[6:7], s[6:7], vcc
	v_cmp_eq_u32_e32 vcc, 64, v22
	s_and_b64 s[6:7], s[6:7], vcc
	v_cmp_eq_u32_e32 vcc, 0, v22
	s_or_b64 s[6:7], s[6:7], vcc
	s_nop 1
	v_cndmask_b32_e64 v50, 0, v50, s[6:7]
	v_add_u32_e32 v51, -1, v25
	v_and_b32_e32 v51, v51, v25
	v_cmp_eq_u32_e32 vcc, 0, v51
	s_mov_b64 s[6:7], vcc
	v_cmp_ne_u32_e32 vcc, 0, v25
	s_and_b64 s[6:7], s[6:7], vcc
	v_cmp_eq_u32_e32 vcc, 64, v24
	s_and_b64 s[6:7], s[6:7], vcc
	v_cmp_eq_u32_e32 vcc, 0, v24
	s_or_b64 s[6:7], s[6:7], vcc
	s_nop 1
	v_cndmask_b32_e64 v50, 0, v50, s[6:7]
	v_add_u32_e32 v51, -1, v27
	v_and_b32_e32 v51, v51, v27
	v_cmp_eq_u32_e32 vcc, 0, v51
	s_mov_b64 s[6:7], vcc
	v_cmp_ne_u32_e32 vcc, 0, v27
	s_and_b64 s[6:7], s[6:7], vcc
	v_cmp_eq_u32_e32 vcc, 64, v26
	s_and_b64 s[6:7], s[6:7], vcc
	v_cmp_eq_u32_e32 vcc, 0, v26
	s_or_b64 s[6:7], s[6:7], vcc
	s_nop 1
	v_cndmask_b32_e64 v50, 0, v50, s[6:7]
	v_add_u32_e32 v51, -1, v29
	v_and_b32_e32 v51, v51, v29
	v_cmp_eq_u32_e32 vcc, 0, v51
	s_mov_b64 s[6:7], vcc
	v_cmp_ne_u32_e32 vcc, 0, v29
	s_and_b64 s[6:7], s[6:7], vcc
	v_cmp_eq_u32_e32 vcc, 64, v28
	s_and_b64 s[6:7], s[6:7], vcc
	v_cmp_eq_u32_e32 vcc, 0, v28
	s_or_b64 s[6:7], s[6:7], vcc
	s_nop 1
	v_cndmask_b32_e64 v50, 0, v50, s[6:7]
	v_add_u32_e32 v51, -1, v31
	v_and_b32_e32 v51, v51, v31
	v_cmp_eq_u32_e32 vcc, 0, v51
	s_mov_b64 s[6:7], vcc
	v_cmp_ne_u32_e32 vcc, 0, v31
	s_and_b64 s[6:7], s[6:7], vcc
	v_cmp_eq_u32_e32 vcc, 64, v30
	s_and_b64 s[6:7], s[6:7], vcc
	v_cmp_eq_u32_e32 vcc, 0, v30
	s_or_b64 s[6:7], s[6:7], vcc
	s_nop 1
	v_cndmask_b32_e64 v50, 0, v50, s[6:7]
	v_add_u32_e32 v51, -1, v33
	v_and_b32_e32 v51, v51, v33
	v_cmp_eq_u32_e32 vcc, 0, v51
	s_mov_b64 s[6:7], vcc
	v_cmp_ne_u32_e32 vcc, 0, v33
	s_and_b64 s[6:7], s[6:7], vcc
	v_cmp_eq_u32_e32 vcc, 64, v32
	s_and_b64 s[6:7], s[6:7], vcc
	v_cmp_eq_u32_e32 vcc, 0, v32
	s_or_b64 s[6:7], s[6:7], vcc
	s_nop 1
	v_cndmask_b32_e64 v50, 0, v50, s[6:7]
	v_add_u32_e32 v51, -1, v35
	v_and_b32_e32 v51, v51, v35
	v_cmp_eq_u32_e32 vcc, 0, v51
	s_mov_b64 s[6:7], vcc
	v_cmp_ne_u32_e32 vcc, 0, v35
	s_and_b64 s[6:7], s[6:7], vcc
	v_cmp_eq_u32_e32 vcc, 64, v34
	s_and_b64 s[6:7], s[6:7], vcc
	v_cmp_eq_u32_e32 vcc, 0, v34
	s_or_b64 s[6:7], s[6:7], vcc
	s_nop 1
	v_cndmask_b32_e64 v50, 0, v50, s[6:7]
	v_add_u32_e32 v51, -1, v37
	v_and_b32_e32 v51, v51, v37
	v_cmp_eq_u32_e32 vcc, 0, v51
	s_mov_b64 s[6:7], vcc
	v_cmp_ne_u32_e32 vcc, 0, v37
	s_and_b64 s[6:7], s[6:7], vcc
	v_cmp_eq_u32_e32 vcc, 64, v36
	s_and_b64 s[6:7], s[6:7], vcc
	v_cmp_eq_u32_e32 vcc, 0, v36
	s_or_b64 s[6:7], s[6:7], vcc
	s_nop 1
	v_cndmask_b32_e64 v50, 0, v50, s[6:7]
	v_add_u32_e32 v51, -1, v39
	v_and_b32_e32 v51, v51, v39
	v_cmp_eq_u32_e32 vcc, 0, v51
	s_mov_b64 s[6:7], vcc
	v_cmp_ne_u32_e32 vcc, 0, v39
	s_and_b64 s[6:7], s[6:7], vcc
	v_cmp_eq_u32_e32 vcc, 64, v38
	s_and_b64 s[6:7], s[6:7], vcc
	v_cmp_eq_u32_e32 vcc, 0, v38
	s_or_b64 s[6:7], s[6:7], vcc
	s_nop 1
	v_cndmask_b32_e64 v50, 0, v50, s[6:7]
	v_add_u32_e32 v51, -1, v41
	v_and_b32_e32 v51, v51, v41
	v_cmp_eq_u32_e32 vcc, 0, v51
	s_mov_b64 s[6:7], vcc
	v_cmp_ne_u32_e32 vcc, 0, v41
	s_and_b64 s[6:7], s[6:7], vcc
	v_cmp_eq_u32_e32 vcc, 64, v40
	s_and_b64 s[6:7], s[6:7], vcc
	v_cmp_eq_u32_e32 vcc, 0, v40
	s_or_b64 s[6:7], s[6:7], vcc
	s_nop 1
	v_cndmask_b32_e64 v50, 0, v50, s[6:7]
	v_add_u32_e32 v51, -1, v43
	v_and_b32_e32 v51, v51, v43
	v_cmp_eq_u32_e32 vcc, 0, v51
	s_mov_b64 s[6:7], vcc
	v_cmp_ne_u32_e32 vcc, 0, v43
	s_and_b64 s[6:7], s[6:7], vcc
	v_cmp_eq_u32_e32 vcc, 64, v42
	s_and_b64 s[6:7], s[6:7], vcc
	v_cmp_eq_u32_e32 vcc, 0, v42
	s_or_b64 s[6:7], s[6:7], vcc
	s_nop 1
	v_cndmask_b32_e64 v50, 0, v50, s[6:7]
	v_add_u32_e32 v51, -1, v45
	v_and_b32_e32 v51, v51, v45
	v_cmp_eq_u32_e32 vcc, 0, v51
	s_mov_b64 s[6:7], vcc
	v_cmp_ne_u32_e32 vcc, 0, v45
	s_and_b64 s[6:7], s[6:7], vcc
	v_cmp_eq_u32_e32 vcc, 64, v44
	s_and_b64 s[6:7], s[6:7], vcc
	v_cmp_eq_u32_e32 vcc, 0, v44
	s_or_b64 s[6:7], s[6:7], vcc
	s_nop 1
	v_cndmask_b32_e64 v50, 0, v50, s[6:7]
	v_add_u32_e32 v51, -1, v47
	v_and_b32_e32 v51, v51, v47
	v_cmp_eq_u32_e32 vcc, 0, v51
	s_mov_b64 s[6:7], vcc
	v_cmp_ne_u32_e32 vcc, 0, v47
	s_and_b64 s[6:7], s[6:7], vcc
	v_cmp_eq_u32_e32 vcc, 64, v46
	s_and_b64 s[6:7], s[6:7], vcc
	v_cmp_eq_u32_e32 vcc, 0, v46
	s_or_b64 s[6:7], s[6:7], vcc
	s_nop 1
	v_cndmask_b32_e64 v50, 0, v50, s[6:7]
	v_add_u32_e32 v51, -1, v49
	v_and_b32_e32 v51, v51, v49
	v_cmp_eq_u32_e32 vcc, 0, v51
	s_mov_b64 s[6:7], vcc
	v_cmp_ne_u32_e32 vcc, 0, v49
	s_and_b64 s[6:7], s[6:7], vcc
	v_cmp_eq_u32_e32 vcc, 64, v48
	s_and_b64 s[6:7], s[6:7], vcc
	v_cmp_eq_u32_e32 vcc, 0, v48
	s_or_b64 s[6:7], s[6:7], vcc
	s_nop 1
	v_cndmask_b32_e64 v50, 0, v50, s[6:7]
	v_readlane_b32 s6, v254, 3
	s_nop 0
	s_cmp_lg_u32 s6, 0
	s_cbranch_scc1 .Lxb_noflag
	ds_write_b32 v193, v50 offset:8
.Lxb_noflag:
.LBB0_369:
	s_mov_b64 s[8:9], exec
	v_mbcnt_lo_u32_b32 v1, s8, 0
	v_mbcnt_hi_u32_b32 v1, s9, v1
	v_cmp_eq_u32_e32 vcc, 0, v1
	s_and_saveexec_b64 s[6:7], vcc
	s_cbranch_execz .LBB0_371
	s_bcnt1_i32_b64 s8, s[8:9]
	v_mov_b32_e32 v3, s8
	v_readlane_b32 s8, v255, 9
	v_readlane_b32 s9, v255, 10
	s_nop 4
	global_atomic_add v3, v193, v3, s[8:9] sc0

; DI unsigned xb_ld(unsigned* p)              { return __hip_atomic_load(p, __ATOMIC_RELAXED, __HIP_MEMORY_SCOPE_AGENT); }
; DI unsigned xb_add(unsigned* p, unsigned v) { return __hip_atomic_fetch_add(p, v, __ATOMIC_RELAXED, __HIP_MEMORY_SCOPE_AGENT); }
; #define XB_SPIN(cond, bar) do { unsigned _sp = 0; while (cond) { __builtin_amdgcn_s_sleep(1); \
;     if ((++_sp & 255u) == 0u) { if (xb_ld(&(bar)[XB_TMO])) break; if (_sp > XB_SPIN_CAP) { atomicAdd(&(bar)[XB_TMO], 1u); break; } } } } while (0)
; DI void xcd_barrier(const XcdBarrier& b) {
;     ...
;         const unsigned old = xb_add(&bar[XB_XSUB(b.x)], 1u);
;         const unsigned gen = old / nloc;
;         if (old + 1u == (gen + 1u) * nloc) {
;             __builtin_amdgcn_fence(__ATOMIC_RELEASE, "agent");
;             asm volatile("s_waitcnt vmcnt(0)" ::: "memory");
;             const unsigned og = xb_add(&bar[XB_TOP], 1u);
;             const unsigned tg = og / nx;
;             if (og + 1u == (tg + 1u) * nx) xb_add(&bar[XB_TOPGEN], 1u);
;             else XB_SPIN(xb_ld(&bar[XB_TOPGEN]) == tg, bar);
.LBB0_385:
	s_andn2_saveexec_b64 s[6:7], s[6:7]
	s_cbranch_execz .LBB0_405
	s_mov_b64 s[6:7], exec
	ds_read_b32 v3, v193 offset:8
	s_add_i32 s8, s52, -1
	s_and_b32 s9, s8, 3
	s_cmp_lt_u32 s9, 2
	s_cselect_b32 s9, s8, 0
	s_waitcnt lgkmcnt(0)
	v_readfirstlane_b32 s8, v3
	s_cmp_lg_u32 s9, 0
	s_cselect_b32 s8, s8, 0
	s_cmp_lg_u32 s8, 0
	s_cbranch_scc1 .LBB0_402
	buffer_wbl2 sc1
	s_waitcnt lgkmcnt(0)
	s_waitcnt vmcnt(0)
	v_mbcnt_lo_u32_b32 v1, s6, 0
	v_mbcnt_hi_u32_b32 v1, s7, v1
	v_cmp_eq_u32_e32 vcc, 0, v1
	s_and_saveexec_b64 s[8:9], vcc
	s_cbranch_execz .LBB0_388
	s_bcnt1_i32_b64 s6, s[6:7]
	v_mov_b32_e32 v2, s6
	v_readlane_b32 s6, v255, 13
	v_readlane_b32 s7, v255, 14
	s_nop 4
	global_atomic_add v2, v193, v2, s[6:7] sc0
